# attn_item MFMA half: K ds_reads and LDS staging write interleaved into PV MFMA gaps, V ds_reads spread 2 per gap in QK burst
# speedup vs baseline: 1.0543x; 1.0112x over previous
; #define LAS __attribute__((address_space(3)))
; __device__ __forceinline__ void attn_item(const Params& p, int l, LAS unsigned char* lds, int b, int h, int J) {
;     ...
; #pragma nounroll
;     for (int j = 0; j < blk_nt; ++j) {
;         LAS unsigned char* cur = lds + (j & 1) * ATT_BUF; LAS unsigned char* nxt = lds + ((j + 1) & 1) * ATT_BUF;
;         const bool more = (j + 1) < blk_nt;
;         if (more) { skn = *(const u32x4*)(gkn + (size_t)(j + 1) * 64 * 512); svt = *(const u32x4*)(gvt + (size_t)(j + 1) * 512 * 64); if (has_kr) skr = *(const u32x4*)(gkr + (size_t)(j + 1) * 64 * 256); }
;         if (j < my_nt) {
;             bf16x8 ka[2][6], va[2][4];
; #pragma unroll
;             for (int kb = 0; kb < 2; ++kb)
; #pragma unroll
;                 for (int s = 0; s < 6; ++s) ka[kb][s] = *(const LAS bf16x8*)(cur + rk + kb * 32 * KROW + 32 * s);
; #pragma unroll
;             for (int dvb = 0; dvb < 2; ++dvb)
; #pragma unroll
;                 for (int ks = 0; ks < 4; ++ks) va[dvb][ks] = *(const LAS bf16x8*)(cur + rv + dvb * 32 * VROW + 32 * ks);
;             __builtin_amdgcn_sched_barrier(0);
;             if (j < my_nt - 1) attn_step<false>(ka, va, qf, 64, lane, o0, o1, mrun, lsum); else attn_step<true>(ka, va, qf, 16, lane, o0, o1, mrun, lsum);
;         }
;         if (more) { *(LAS u32x4*)(nxt + wkn) = skn; *(LAS u32x4*)(nxt + wvt) = svt; if (has_kr) *(LAS u32x4*)(nxt + wkr) = skr; }
.Latt_head:
	s_add_i32 s12, s13, 1
	s_cmp_ge_i32 s13, s11
	s_cbranch_scc1 .Latt_skip_e
	s_bitcmp1_b32 s13, 0
	s_cselect_b32 s14, 0x5800, 0
	s_add_i32 s14, s14, 0
	v_add3_u32 v0, s14, v233, v236
	s_cmp_eq_u32 s13, 0
	s_cbranch_scc1 .Latt_first
	v_mfma_f32_32x32x16_bf16 v[18:33], v[158:161], v[82:85], v[18:33]
	ds_read_b128 v[186:189], v0
	ds_read_b128 v[182:185], v0 offset:32
	v_mfma_f32_32x32x16_bf16 v[2:17], v[162:165], v[82:85], v[2:17]
	ds_read_b128 v[178:181], v0 offset:64
	ds_read_b128 v[174:177], v0 offset:96
	v_mfma_f32_32x32x16_bf16 v[18:33], v[150:153], v[86:89], v[18:33]
	ds_read_b128 v[170:173], v0 offset:128
	ds_read_b128 v[166:169], v0 offset:160
	v_mfma_f32_32x32x16_bf16 v[2:17], v[154:157], v[86:89], v[2:17]
	ds_read_b128 v[50:53], v0 offset:6656
	ds_read_b128 v[206:209], v0 offset:6688
	v_mfma_f32_32x32x16_bf16 v[18:33], v[146:149], v[90:93], v[18:33]
	ds_read_b128 v[202:205], v0 offset:6720
	ds_read_b128 v[198:201], v0 offset:6752
	v_mfma_f32_32x32x16_bf16 v[2:17], v[142:145], v[90:93], v[2:17]
	ds_read_b128 v[194:197], v0 offset:6784
	ds_read_b128 v[190:193], v0 offset:6816
	s_cmp_lt_i32 s12, s5
	s_cbranch_scc0 .Latt_noe_h1
	s_bitcmp1_b32 s12, 0
	s_cselect_b32 s15, 0x5800, 0
	v_add_u32_e32 v0, s15, v234
	s_waitcnt vmcnt(1)
	ds_write_b128 v0, v[98:101]
	v_add_u32_e32 v0, s15, v238
	s_waitcnt vmcnt(0)
	ds_write_b128 v0, v[102:105] offset:13312
	s_and_saveexec_b64 s[50:51], s[40:41]
	v_add_u32_e32 v0, s15, v239
	ds_write_b128 v0, v[106:109] offset:128
	s_or_b64 exec, exec, s[50:51]
.Latt_noe_h1:
	v_mfma_f32_32x32x16_bf16 v[18:33], v[138:141], v[94:97], v[18:33]
	v_mfma_f32_32x32x16_bf16 v[2:17], v[134:137], v[94:97], v[2:17]
	s_branch .Latt_nopv
.Latt_first:
	ds_read_b128 v[186:189], v0
	ds_read_b128 v[182:185], v0 offset:32
	ds_read_b128 v[178:181], v0 offset:64
	ds_read_b128 v[174:177], v0 offset:96
	ds_read_b128 v[170:173], v0 offset:128
	ds_read_b128 v[166:169], v0 offset:160
	ds_read_b128 v[50:53], v0 offset:6656
	ds_read_b128 v[206:209], v0 offset:6688
	ds_read_b128 v[202:205], v0 offset:6720
	ds_read_b128 v[198:201], v0 offset:6752
	ds_read_b128 v[194:197], v0 offset:6784
	ds_read_b128 v[190:193], v0 offset:6816
	s_cmp_lt_i32 s12, s5
	s_cbranch_scc0 .Latt_noe_first
	s_bitcmp1_b32 s12, 0
	s_cselect_b32 s15, 0x5800, 0
	v_add_u32_e32 v0, s15, v234
	s_waitcnt vmcnt(1)
	ds_write_b128 v0, v[98:101]
	v_add_u32_e32 v0, s15, v238
	s_waitcnt vmcnt(0)
	ds_write_b128 v0, v[102:105] offset:13312
	s_and_saveexec_b64 s[50:51], s[40:41]
	v_add_u32_e32 v0, s15, v239
	ds_write_b128 v0, v[106:109] offset:128
	s_or_b64 exec, exec, s[50:51]
.Latt_noe_first:
.Latt_nopv:
	v_add3_u32 v0, s14, v237, v236
	s_cmp_gt_i32 s13, s10
	s_cbranch_scc1 .Latt_masked
	s_waitcnt lgkmcnt(0)
	v_mfma_f32_32x32x16_bf16 v[66:81], v[186:189], v[110:113], v[34:49]
	v_mfma_f32_32x32x16_bf16 v[66:81], v[182:185], v[114:117], v[66:81]
	v_mfma_f32_32x32x16_bf16 v[50:65], v[50:53], v[110:113], v[34:49]
	v_mfma_f32_32x32x16_bf16 v[66:81], v[178:181], v[118:121], v[66:81]
	v_mfma_f32_32x32x16_bf16 v[50:65], v[206:209], v[114:117], v[50:65]
	ds_read_b128 v[158:161], v0 offset:13312
	ds_read_b128 v[150:153], v0 offset:13344
	v_mfma_f32_32x32x16_bf16 v[66:81], v[174:177], v[122:125], v[66:81]
	ds_read_b128 v[146:149], v0 offset:13376
	ds_read_b128 v[138:141], v0 offset:13408
	v_mfma_f32_32x32x16_bf16 v[50:65], v[202:205], v[118:121], v[50:65]
	ds_read_b128 v[162:165], v0 offset:17920
	ds_read_b128 v[154:157], v0 offset:17952
	v_mfma_f32_32x32x16_bf16 v[66:81], v[170:173], v[126:129], v[66:81]
	ds_read_b128 v[142:145], v0 offset:17984
	ds_read_b128 v[134:137], v0 offset:18016
	v_mfma_f32_32x32x16_bf16 v[50:65], v[198:201], v[122:125], v[50:65]
	v_mfma_f32_32x32x16_bf16 v[66:81], v[166:169], v[130:133], v[66:81]
	v_mfma_f32_32x32x16_bf16 v[50:65], v[194:197], v[126:129], v[50:65]
	v_mfma_f32_32x32x16_bf16 v[50:65], v[190:193], v[130:133], v[50:65]
	s_waitcnt lgkmcnt(0)
	s_barrier
	s_add_i32 s14, s12, 1
	s_cmp_lt_i32 s14, s5
	s_cbranch_scc0 .Latt_nold_main
	global_load_dwordx4 v[98:101], v[242:243], off
	global_load_dwordx4 v[102:105], v[244:245], off
	s_and_saveexec_b64 s[50:51], s[40:41]
	s_cbranch_execz .Latt_ldx_main
	global_load_dwordx4 v[106:109], v[240:241], off

; #define LAS __attribute__((address_space(3)))
; __device__ __forceinline__ void attn_item(const Params& p, int l, LAS unsigned char* lds, int b, int h, int J) {
;     ...
;         if (more) { skn = *(const u32x4*)(gkn + (size_t)(j + 1) * 64 * 512); svt = *(const u32x4*)(gvt + (size_t)(j + 1) * 512 * 64); if (has_kr) skr = *(const u32x4*)(gkr + (size_t)(j + 1) * 64 * 256); }
;     ...
;         if (more) { *(LAS u32x4*)(nxt + wkn) = skn; *(LAS u32x4*)(nxt + wvt) = svt; if (has_kr) *(LAS u32x4*)(nxt + wkr) = skr; }
;         __syncthreads();
.Latt_skip_e:
	s_cmp_lt_i32 s12, s5
	s_cbranch_scc0 .Latt_noe_skip
	s_bitcmp1_b32 s12, 0
	s_cselect_b32 s15, 0x5800, 0
	v_add_u32_e32 v0, s15, v234
	s_waitcnt vmcnt(1)
	ds_write_b128 v0, v[98:101]
	v_add_u32_e32 v0, s15, v238
	s_waitcnt vmcnt(0)
	ds_write_b128 v0, v[102:105] offset:13312
	s_and_saveexec_b64 s[50:51], s[40:41]
	v_add_u32_e32 v0, s15, v239
	ds_write_b128 v0, v[106:109] offset:128
	s_or_b64 exec, exec, s[50:51]
.Latt_noe_skip:
.Latt_skip:
	s_waitcnt lgkmcnt(0)
	s_barrier
	s_add_i32 s14, s12, 1
	s_cmp_lt_i32 s14, s5
	s_cbranch_scc0 .Latt_nold_skip
	global_load_dwordx4 v[98:101], v[242:243], off
	global_load_dwordx4 v[102:105], v[244:245], off
	s_and_saveexec_b64 s[50:51], s[40:41]
	s_cbranch_execz .Latt_ldx_skip
	global_load_dwordx4 v[106:109], v[240:241], off
